# refine: rank of the threshold-bin candidates via lane broadcasts and one 64-bit compare per candidate when a query has at most 64 of them
# speedup vs baseline: 1.0022x; 1.0022x over previous
.LBB0_1147:
	s_cmp_gt_i32 s13, 64
	s_cbranch_scc1 .Lrf0_gen
	s_add_i32 s1, s13, 1
	s_and_b32 s1, s1, -2
	s_sub_i32 s14, s13, s1
	v_mov_b32_e32 v12, s14
	v_mov_b32_e32 v11, 0
	v_mov_b32_e32 v10, 0
	v_mov_b32_e32 v9, 0
	s_mov_b32 s0, 0
	s_waitcnt lgkmcnt(0)
.Lrf0_loop:
	v_readlane_b32 s58, v6, s0
	v_readlane_b32 s59, v7, s0
	s_add_i32 s14, s0, 1
	v_readlane_b32 s52, v6, s14
	v_readlane_b32 s53, v7, s14
	s_add_i32 s0, s0, 2
	s_cmp_lt_i32 s0, s1
	v_cmp_gt_u64_e32 vcc, s[58:59], v[6:7]
	v_cmp_gt_u64_e64 s[56:57], s[52:53], v[6:7]
	s_nop 0
	v_addc_co_u32_e32 v12, vcc, 0, v12, vcc
	v_addc_co_u32_e64 v12, s[56:57], 0, v12, s[56:57]
	s_cbranch_scc1 .Lrf0_loop
	s_mov_b64 vcc, 0
	s_mov_b64 s[56:57], 0
	s_mov_b64 s[52:53], 0
	s_branch .LBB0_1157

.LBB0_1172:
	s_cmp_gt_i32 s13, 64
	s_cbranch_scc1 .Lrf1_gen
	s_add_i32 s1, s13, 1
	s_and_b32 s1, s1, -2
	s_sub_i32 s5, s13, s1
	v_mov_b32_e32 v12, s5
	v_mov_b32_e32 v11, 0
	v_mov_b32_e32 v10, 0
	v_mov_b32_e32 v9, 0
	s_mov_b32 s0, 0
	s_waitcnt lgkmcnt(0)
.Lrf1_loop:
	v_readlane_b32 s58, v6, s0
	v_readlane_b32 s59, v7, s0
	s_add_i32 s5, s0, 1
	v_readlane_b32 s52, v6, s5
	v_readlane_b32 s53, v7, s5
	s_add_i32 s0, s0, 2
	s_cmp_lt_i32 s0, s1
	v_cmp_gt_u64_e32 vcc, s[58:59], v[6:7]
	v_cmp_gt_u64_e64 s[54:55], s[52:53], v[6:7]
	s_nop 0
	v_addc_co_u32_e32 v12, vcc, 0, v12, vcc
	v_addc_co_u32_e64 v12, s[54:55], 0, v12, s[54:55]
	s_cbranch_scc1 .Lrf1_loop
	s_mov_b64 vcc, 0
	s_mov_b64 s[54:55], 0
	s_mov_b64 s[52:53], 0
	s_branch .LBB0_1182

.LBB0_1197:
	s_cmp_gt_i32 s5, 64
	s_cbranch_scc1 .Lrf2_gen
	s_add_i32 s1, s5, 1
	s_and_b32 s1, s1, -2
	s_sub_i32 s4, s5, s1
	v_mov_b32_e32 v12, s4
	v_mov_b32_e32 v11, 0
	v_mov_b32_e32 v10, 0
	v_mov_b32_e32 v9, 0
	s_mov_b32 s0, 0
	s_waitcnt lgkmcnt(0)
.Lrf2_loop:
	v_readlane_b32 s58, v6, s0
	v_readlane_b32 s59, v7, s0
	s_add_i32 s4, s0, 1
	v_readlane_b32 s52, v6, s4
	v_readlane_b32 s53, v7, s4
	s_add_i32 s0, s0, 2
	s_cmp_lt_i32 s0, s1
	v_cmp_gt_u64_e32 vcc, s[58:59], v[6:7]
	v_cmp_gt_u64_e64 s[54:55], s[52:53], v[6:7]
	s_nop 0
	v_addc_co_u32_e32 v12, vcc, 0, v12, vcc
	v_addc_co_u32_e64 v12, s[54:55], 0, v12, s[54:55]
	s_cbranch_scc1 .Lrf2_loop
	s_mov_b64 vcc, 0
	s_mov_b64 s[54:55], 0
	s_mov_b64 s[52:53], 0
	s_branch .LBB0_1207

.LBB0_1222:
	s_cmp_gt_i32 s4, 64
	s_cbranch_scc1 .Lrf3_gen
	s_add_i32 s1, s4, 1
	s_and_b32 s1, s1, -2
	s_sub_i32 s3, s4, s1
	v_mov_b32_e32 v11, s3
	v_mov_b32_e32 v10, 0
	v_mov_b32_e32 v9, 0
	v_mov_b32_e32 v8, 0
	s_mov_b32 s0, 0
	s_waitcnt lgkmcnt(0)
.Lrf3_loop:
	v_readlane_b32 s58, v6, s0
	v_readlane_b32 s59, v7, s0
	s_add_i32 s3, s0, 1
	v_readlane_b32 s52, v6, s3
	v_readlane_b32 s53, v7, s3
	s_add_i32 s0, s0, 2
	s_cmp_lt_i32 s0, s1
	v_cmp_gt_u64_e32 vcc, s[58:59], v[6:7]
	v_cmp_gt_u64_e64 s[54:55], s[52:53], v[6:7]
	s_nop 0
	v_addc_co_u32_e32 v11, vcc, 0, v11, vcc
	v_addc_co_u32_e64 v11, s[54:55], 0, v11, s[54:55]
	s_cbranch_scc1 .Lrf3_loop
	s_mov_b64 vcc, 0
	s_mov_b64 s[54:55], 0
	s_mov_b64 s[52:53], 0
	s_branch .LBB0_1232
